# same B0-read rebalancing applied to the down and gemm1 K-loops as well
# speedup vs baseline: 1.0073x; 1.0031x over previous
; #define G8_STAGE(bufoff, gbase) do { _Pragma("unroll") for (int _i = 0; _i < 2; ++_i) \
;     __builtin_amdgcn_global_load_lds((const unsigned*)((const char*)(gbase) + voffA[_i]), (LAS unsigned*)(lds + (bufoff) + ldsw + _i * 8192), 16, 0, 0); } while (0)
; #define G8_LDA(dst, b, h) do { _Pragma("unroll") for (int m = 0; m < 4; ++m) _Pragma("unroll") for (int k = 0; k < 2; ++k) dst[m][k] = *(const LAS h16x8*)(lds + G8_SA(b, h) + aoff + m * 2048 + k * 1024); } while (0)
; #define G8_LDB(dst, b, h) do { _Pragma("unroll") for (int n = 0; n < 2; ++n) _Pragma("unroll") for (int k = 0; k < 2; ++k) dst[n][k] = *(const LAS h16x8*)(lds + G8_SB(b, h) + boff + n * 2048 + k * 1024); } while (0)
; #define G8_MMA(ai, bj, At, Bt_) do { __builtin_amdgcn_s_setprio(1); _Pragma("unroll") for (int m = 0; m < 4; ++m) _Pragma("unroll") for (int n = 0; n < 2; ++n) _Pragma("unroll") for (int k = 0; k < 2; ++k) \
;     acc[ai][bj][m][n] = __builtin_amdgcn_mfma_f32_16x16x32_f16(Bt_[n][k], At[m][k], acc[ai][bj][m][n], 0, 0, 0); __builtin_amdgcn_s_setprio(0); } while (0)
; #define G8_WAIT_L(n) asm volatile("s_waitcnt lgkmcnt(" #n ")" ::: "memory")
; #define G8_BAR __builtin_amdgcn_s_barrier()
; #define G8_SCHED __builtin_amdgcn_sched_barrier(0)
; template <class Epi>
; __device__ __forceinline__ void gemm_phase(LAS unsigned char* lds, const h16* A, const h16* Bt, int K, const Order& S, const Epi& E) {
;     ...
;     const bool has_next = S.next(ui + 1, nxt);
;     const char* nA = has_next ? (const char*)A + (size_t)nxt.pm * tstep : cA;
;     const char* nB = has_next ? (const char*)Bt + (size_t)nxt.pn * tstep : cB;
;     for (int t = 0; t < nt; t += 2) {
;       const bool last = (t == nt - 2);
;       const char* a1 = cA + (size_t)(t + 1) * kstep;
;       const char* a2 = last ? nA : cA + (size_t)(t + 2) * kstep;
;       const char* b2 = last ? nB : cB + (size_t)(t + 2) * kstep;
;       const char* a3 = a2 + kstep;
;       const char* b3 = b2 + kstep;
;       if (Epi::MID_T >= 0 && t == Epi::MID_T) E.mid(acc, ui, wr, fr);
;       G8_LDB(B0, 0, 0); G8_SCHED; G8_LDA(At, 0, 0); G8_STAGE(G8_SA(1, 1), a1 + hstep);
;       G8_WAIT_L(8); G8_BAR; G8_WAIT_L(0); G8_MMA(0, 0, At, B0); G8_BAR; G8_SCHED;
.LBB0_194:
	v_mov_b64_e32 v[2:3], 0x380
	s_ashr_i32 s19, s18, 31
	v_cmp_lt_i64_e32 vcc, s[14:15], v[2:3]
	s_lshl_b64 s[14:15], s[18:19], 19
	s_add_u32 s20, s29, s14
	s_addc_u32 s21, s30, s15
	s_and_b64 s[14:15], vcc, exec
	s_cselect_b32 s19, s21, s57
	s_cselect_b32 s25, s20, s56
	s_ashr_i32 s17, s16, 31
	s_lshl_b64 s[14:15], s[16:17], 19
	s_add_u32 s22, s31, s14
	s_addc_u32 s23, s34, s15
	s_and_b64 s[14:15], vcc, exec
	s_cselect_b32 s17, s23, s55
	s_cselect_b32 s26, s22, s54
	s_add_u32 s10, s56, 0x40080
	s_addc_u32 s11, s57, 0
	s_add_u32 s27, s54, 0x100
	v_mov_b32_e32 v2, 0
	s_addc_u32 s53, s55, 0
	s_mov_b32 s54, -2
	v_mov_b32_e32 v3, v2
	v_mov_b32_e32 v4, v2
	v_mov_b32_e32 v5, v2
	v_mov_b32_e32 v6, v2
	v_mov_b32_e32 v7, v2
	v_mov_b32_e32 v8, v2
	v_mov_b32_e32 v9, v2
	v_mov_b32_e32 v18, v2
	v_mov_b32_e32 v19, v2
	v_mov_b32_e32 v20, v2
	v_mov_b32_e32 v21, v2
	v_mov_b32_e32 v22, v2
	v_mov_b32_e32 v23, v2
	v_mov_b32_e32 v24, v2
	v_mov_b32_e32 v25, v2
	v_mov_b32_e32 v34, v2
	v_mov_b32_e32 v35, v2
	v_mov_b32_e32 v36, v2
	v_mov_b32_e32 v37, v2
	v_mov_b32_e32 v38, v2
	v_mov_b32_e32 v39, v2
	v_mov_b32_e32 v40, v2
	v_mov_b32_e32 v41, v2
	v_mov_b32_e32 v50, v2
	v_mov_b32_e32 v51, v2
	v_mov_b32_e32 v52, v2
	v_mov_b32_e32 v53, v2
	v_mov_b32_e32 v54, v2
	v_mov_b32_e32 v55, v2
	v_mov_b32_e32 v56, v2
	v_mov_b32_e32 v57, v2
	v_mov_b32_e32 v10, v2
	v_mov_b32_e32 v11, v2
	v_mov_b32_e32 v12, v2
	v_mov_b32_e32 v13, v2
	v_mov_b32_e32 v14, v2
	v_mov_b32_e32 v15, v2
	v_mov_b32_e32 v16, v2
	v_mov_b32_e32 v17, v2
	v_mov_b32_e32 v26, v2
	v_mov_b32_e32 v27, v2
	v_mov_b32_e32 v28, v2
	v_mov_b32_e32 v29, v2
	v_mov_b32_e32 v30, v2
	v_mov_b32_e32 v31, v2
	v_mov_b32_e32 v32, v2
	v_mov_b32_e32 v33, v2
	v_mov_b32_e32 v42, v2
	v_mov_b32_e32 v43, v2
	v_mov_b32_e32 v44, v2
	v_mov_b32_e32 v45, v2
	v_mov_b32_e32 v46, v2
	v_mov_b32_e32 v47, v2
	v_mov_b32_e32 v48, v2
	v_mov_b32_e32 v49, v2
	v_mov_b32_e32 v58, v2
	v_mov_b32_e32 v59, v2
	v_mov_b32_e32 v60, v2
	v_mov_b32_e32 v61, v2
	v_mov_b32_e32 v62, v2
	v_mov_b32_e32 v63, v2
	v_mov_b32_e32 v64, v2
	v_mov_b32_e32 v65, v2
	v_mov_b32_e32 v66, v2
	v_mov_b32_e32 v67, v2
	v_mov_b32_e32 v68, v2
	v_mov_b32_e32 v69, v2
	v_mov_b32_e32 v70, v2
	v_mov_b32_e32 v71, v2
	v_mov_b32_e32 v72, v2
	v_mov_b32_e32 v73, v2
	v_mov_b32_e32 v82, v2
	v_mov_b32_e32 v83, v2
	v_mov_b32_e32 v84, v2
	v_mov_b32_e32 v85, v2
	v_mov_b32_e32 v86, v2
	v_mov_b32_e32 v87, v2
	v_mov_b32_e32 v88, v2
	v_mov_b32_e32 v89, v2
	v_mov_b32_e32 v98, v2
	v_mov_b32_e32 v99, v2
	v_mov_b32_e32 v100, v2
	v_mov_b32_e32 v101, v2
	v_mov_b32_e32 v102, v2
	v_mov_b32_e32 v103, v2
	v_mov_b32_e32 v104, v2
	v_mov_b32_e32 v105, v2
	v_mov_b32_e32 v114, v2
	v_mov_b32_e32 v115, v2
	v_mov_b32_e32 v116, v2
	v_mov_b32_e32 v117, v2
	v_mov_b32_e32 v118, v2
	v_mov_b32_e32 v119, v2
	v_mov_b32_e32 v120, v2
	v_mov_b32_e32 v121, v2
	v_mov_b32_e32 v74, v2
	v_mov_b32_e32 v75, v2
	v_mov_b32_e32 v76, v2
	v_mov_b32_e32 v77, v2
	v_mov_b32_e32 v78, v2
	v_mov_b32_e32 v79, v2
	v_mov_b32_e32 v80, v2
	v_mov_b32_e32 v81, v2
	v_mov_b32_e32 v90, v2
	v_mov_b32_e32 v91, v2
	v_mov_b32_e32 v92, v2
	v_mov_b32_e32 v93, v2
	v_mov_b32_e32 v94, v2
	v_mov_b32_e32 v95, v2
	v_mov_b32_e32 v96, v2
	v_mov_b32_e32 v97, v2
	v_mov_b32_e32 v106, v2
	v_mov_b32_e32 v107, v2
	v_mov_b32_e32 v108, v2
	v_mov_b32_e32 v109, v2
	v_mov_b32_e32 v110, v2
	v_mov_b32_e32 v111, v2
	v_mov_b32_e32 v112, v2
	v_mov_b32_e32 v113, v2
	v_mov_b32_e32 v122, v2
	v_mov_b32_e32 v123, v2
	v_mov_b32_e32 v124, v2
	v_mov_b32_e32 v125, v2
	v_mov_b32_e32 v126, v2
	v_mov_b32_e32 v127, v2
	v_mov_b32_e32 v128, v2
	v_mov_b32_e32 v129, v2
	ds_read_b128 v[152:155], v161
	ds_read_b128 v[178:181], v162
	ds_read_b128 v[182:185], v163
	ds_read_b128 v[186:189], v164
.LBB0_195:
	s_add_u32 s12, s10, 0xfffc0080
	s_addc_u32 s13, s11, -1
	s_cmp_eq_u32 s54, 12
	s_cselect_b32 s15, s19, s13
	s_cselect_b32 s14, s25, s12
	s_cselect_b32 s13, s17, s53
	s_cselect_b32 s12, s26, s27
	s_mov_b32 m0, s50
	v_lshl_add_u64 v[140:141], s[10:11], 0, v[136:137]
	ds_read_b128 v[202:205], v159
	ds_read_b128 v[206:209], v159 offset:1024
	ds_read_b128 v[210:213], v159 offset:2048
	ds_read_b128 v[214:217], v159 offset:3072
	ds_read_b128 v[218:221], v159 offset:4096
	ds_read_b128 v[222:225], v159 offset:5120
	ds_read_b128 v[226:229], v159 offset:6144
	ds_read_b128 v[230:233], v159 offset:7168
	global_load_lds_dwordx4 v[140:141], off
	v_lshl_add_u64 v[140:141], s[10:11], 0, v[138:139]
	s_mov_b32 m0, s51
	s_nop 0
	global_load_lds_dwordx4 v[140:141], off
	s_waitcnt lgkmcnt(8)
	s_barrier
	s_waitcnt lgkmcnt(0)
	s_setprio 1
	s_waitcnt lgkmcnt(0)
	v_mfma_f32_16x16x32_f16 v[126:129], v[152:155], v[202:205], v[126:129]
	v_mfma_f32_16x16x32_f16 v[122:125], v[182:185], v[202:205], v[122:125]
	v_mfma_f32_16x16x32_f16 v[110:113], v[152:155], v[210:213], v[110:113]
	v_mfma_f32_16x16x32_f16 v[106:109], v[182:185], v[210:213], v[106:109]
	v_mfma_f32_16x16x32_f16 v[94:97], v[152:155], v[218:221], v[94:97]
	v_mfma_f32_16x16x32_f16 v[90:93], v[182:185], v[218:221], v[90:93]
	v_mfma_f32_16x16x32_f16 v[78:81], v[152:155], v[226:229], v[78:81]
	v_mfma_f32_16x16x32_f16 v[74:77], v[182:185], v[226:229], v[74:77]
	v_mfma_f32_16x16x32_f16 v[126:129], v[178:181], v[206:209], v[126:129]
	v_mfma_f32_16x16x32_f16 v[122:125], v[186:189], v[206:209], v[122:125]
	v_mfma_f32_16x16x32_f16 v[110:113], v[178:181], v[214:217], v[110:113]
	v_mfma_f32_16x16x32_f16 v[106:109], v[186:189], v[214:217], v[106:109]
	v_mfma_f32_16x16x32_f16 v[94:97], v[178:181], v[222:225], v[94:97]
	v_mfma_f32_16x16x32_f16 v[90:93], v[186:189], v[222:225], v[90:93]
	v_mfma_f32_16x16x32_f16 v[78:81], v[178:181], v[230:233], v[78:81]
	v_mfma_f32_16x16x32_f16 v[74:77], v[186:189], v[230:233], v[74:77]
	s_setprio 0
	s_barrier
; #define G8_STAGE(bufoff, gbase) do { _Pragma("unroll") for (int _i = 0; _i < 2; ++_i) \
;     __builtin_amdgcn_global_load_lds((const unsigned*)((const char*)(gbase) + voffA[_i]), (LAS unsigned*)(lds + (bufoff) + ldsw + _i * 8192), 16, 0, 0); } while (0)
; #define G8_LDA(dst, b, h) do { _Pragma("unroll") for (int m = 0; m < 4; ++m) _Pragma("unroll") for (int k = 0; k < 2; ++k) dst[m][k] = *(const LAS h16x8*)(lds + G8_SA(b, h) + aoff + m * 2048 + k * 1024); } while (0)
; #define G8_LDB(dst, b, h) do { _Pragma("unroll") for (int n = 0; n < 2; ++n) _Pragma("unroll") for (int k = 0; k < 2; ++k) dst[n][k] = *(const LAS h16x8*)(lds + G8_SB(b, h) + boff + n * 2048 + k * 1024); } while (0)
; #define G8_MMA(ai, bj, At, Bt_) do { __builtin_amdgcn_s_setprio(1); _Pragma("unroll") for (int m = 0; m < 4; ++m) _Pragma("unroll") for (int n = 0; n < 2; ++n) _Pragma("unroll") for (int k = 0; k < 2; ++k) \
;     acc[ai][bj][m][n] = __builtin_amdgcn_mfma_f32_16x16x32_f16(Bt_[n][k], At[m][k], acc[ai][bj][m][n], 0, 0, 0); __builtin_amdgcn_s_setprio(0); } while (0)
; #define G8_WAIT_V(n) asm volatile("s_waitcnt vmcnt(" #n ")" ::: "memory")
; #define G8_WAIT_L(n) asm volatile("s_waitcnt lgkmcnt(" #n ")" ::: "memory")
; #define G8_BAR __builtin_amdgcn_s_barrier()
; #define G8_SCHED __builtin_amdgcn_sched_barrier(0)
; template <class Epi>
; __device__ __forceinline__ void gemm_phase(LAS unsigned char* lds, const h16* A, const h16* Bt, int K, const Order& S, const Epi& E) {
;     ...
;       G8_LDB(B1, 0, 1); G8_STAGE(G8_SB(0, 0), b2);
;       G8_BAR; G8_WAIT_L(0); G8_MMA(0, 1, At, B1); G8_BAR;
;       G8_LDA(At, 0, 1); G8_STAGE(G8_SA(0, 0), a2);
;       G8_BAR; G8_WAIT_L(0); G8_MMA(1, 0, At, B0); G8_BAR; G8_SCHED;
;       G8_STAGE(G8_SB(0, 1), b2 + hstep);
;       G8_WAIT_V(6); G8_BAR; G8_MMA(1, 1, At, B1); G8_BAR;
;       G8_LDB(B0, 1, 0); G8_SCHED; G8_LDA(At, 1, 0); G8_STAGE(G8_SA(0, 1), a2 + hstep);
;       G8_WAIT_L(8); G8_BAR; G8_WAIT_L(0); G8_MMA(0, 0, At, B0); G8_BAR; G8_SCHED;
	s_mov_b32 m0, s36
	v_lshl_add_u64 v[140:141], s[12:13], 0, v[132:133]
	ds_read_b128 v[234:237], v165
	ds_read_b128 v[238:241], v166
	ds_read_b128 v[242:245], v167
	ds_read_b128 v[246:249], v168
	global_load_lds_dwordx4 v[140:141], off
	v_lshl_add_u64 v[156:157], s[12:13], 0, v[130:131]
	s_mov_b32 m0, s37
	s_nop 0
	global_load_lds_dwordx4 v[156:157], off
	s_barrier
	s_waitcnt lgkmcnt(0)
	s_setprio 1
	s_waitcnt lgkmcnt(0)
	v_mfma_f32_16x16x32_f16 v[118:121], v[234:237], v[202:205], v[118:121]
	v_mfma_f32_16x16x32_f16 v[114:117], v[242:245], v[202:205], v[114:117]
	v_mfma_f32_16x16x32_f16 v[102:105], v[234:237], v[210:213], v[102:105]
	v_mfma_f32_16x16x32_f16 v[98:101], v[242:245], v[210:213], v[98:101]
	v_mfma_f32_16x16x32_f16 v[86:89], v[234:237], v[218:221], v[86:89]
	v_mfma_f32_16x16x32_f16 v[82:85], v[242:245], v[218:221], v[82:85]
	v_mfma_f32_16x16x32_f16 v[70:73], v[234:237], v[226:229], v[70:73]
	v_mfma_f32_16x16x32_f16 v[66:69], v[242:245], v[226:229], v[66:69]
	v_mfma_f32_16x16x32_f16 v[118:121], v[238:241], v[206:209], v[118:121]
	v_mfma_f32_16x16x32_f16 v[114:117], v[246:249], v[206:209], v[114:117]
	v_mfma_f32_16x16x32_f16 v[102:105], v[238:241], v[214:217], v[102:105]
	v_mfma_f32_16x16x32_f16 v[98:101], v[246:249], v[214:217], v[98:101]
	v_mfma_f32_16x16x32_f16 v[86:89], v[238:241], v[222:225], v[86:89]
	v_mfma_f32_16x16x32_f16 v[82:85], v[246:249], v[222:225], v[82:85]
	v_mfma_f32_16x16x32_f16 v[70:73], v[238:241], v[230:233], v[70:73]
	v_mfma_f32_16x16x32_f16 v[66:69], v[246:249], v[230:233], v[66:69]
	s_setprio 0
	s_mov_b32 m0, s35
	v_lshl_add_u64 v[250:251], s[14:15], 0, v[132:133]
	s_barrier
	ds_read_b128 v[202:205], v159 offset:16384
	ds_read_b128 v[206:209], v159 offset:17408
	ds_read_b128 v[210:213], v159 offset:18432
	ds_read_b128 v[214:217], v159 offset:19456
	ds_read_b128 v[218:221], v159 offset:20480
	ds_read_b128 v[222:225], v159 offset:21504
	ds_read_b128 v[226:229], v159 offset:22528
	ds_read_b128 v[230:233], v159 offset:23552
	global_load_lds_dwordx4 v[250:251], off
	v_lshl_add_u64 v[252:253], s[14:15], 0, v[130:131]
	s_mov_b32 m0, s38
	s_nop 0
	global_load_lds_dwordx4 v[252:253], off
	s_waitcnt vmcnt(10)
	s_barrier
	s_waitcnt lgkmcnt(0)
	s_setprio 1
	s_waitcnt lgkmcnt(0)
	v_mfma_f32_16x16x32_f16 v[62:65], v[152:155], v[202:205], v[62:65]
	v_mfma_f32_16x16x32_f16 v[58:61], v[182:185], v[202:205], v[58:61]
	v_mfma_f32_16x16x32_f16 v[46:49], v[152:155], v[210:213], v[46:49]
	v_mfma_f32_16x16x32_f16 v[42:45], v[182:185], v[210:213], v[42:45]
	v_mfma_f32_16x16x32_f16 v[30:33], v[152:155], v[218:221], v[30:33]
	v_mfma_f32_16x16x32_f16 v[26:29], v[182:185], v[218:221], v[26:29]
	v_mfma_f32_16x16x32_f16 v[14:17], v[152:155], v[226:229], v[14:17]
	v_mfma_f32_16x16x32_f16 v[10:13], v[182:185], v[226:229], v[10:13]
	v_mfma_f32_16x16x32_f16 v[62:65], v[178:181], v[206:209], v[62:65]
	v_mfma_f32_16x16x32_f16 v[58:61], v[186:189], v[206:209], v[58:61]
	v_mfma_f32_16x16x32_f16 v[46:49], v[178:181], v[214:217], v[46:49]
	v_mfma_f32_16x16x32_f16 v[42:45], v[186:189], v[214:217], v[42:45]
	v_mfma_f32_16x16x32_f16 v[30:33], v[178:181], v[222:225], v[30:33]
	v_mfma_f32_16x16x32_f16 v[26:29], v[186:189], v[222:225], v[26:29]
	v_mfma_f32_16x16x32_f16 v[14:17], v[178:181], v[230:233], v[14:17]
	v_mfma_f32_16x16x32_f16 v[10:13], v[186:189], v[230:233], v[10:13]
	s_setprio 0
	s_barrier
	s_add_u32 s56, s12, 0x40000
	s_addc_u32 s57, s13, 0
	s_mov_b32 m0, s39
	v_lshl_add_u64 v[152:153], s[56:57], 0, v[132:133]
	global_load_lds_dwordx4 v[152:153], off
	v_lshl_add_u64 v[152:153], s[56:57], 0, v[130:131]
	s_mov_b32 m0, s40
	s_nop 0
	global_load_lds_dwordx4 v[152:153], off
	ds_read_b128 v[152:155], v169
	ds_read_b128 v[178:181], v170
	ds_read_b128 v[182:185], v171
	ds_read_b128 v[186:189], v172
	s_waitcnt vmcnt(6)
	s_barrier
	s_setprio 1
	v_mfma_f32_16x16x32_f16 v[54:57], v[234:237], v[202:205], v[54:57]
	v_mfma_f32_16x16x32_f16 v[50:53], v[242:245], v[202:205], v[50:53]
	v_mfma_f32_16x16x32_f16 v[38:41], v[234:237], v[210:213], v[38:41]
	v_mfma_f32_16x16x32_f16 v[34:37], v[242:245], v[210:213], v[34:37]
	v_mfma_f32_16x16x32_f16 v[22:25], v[234:237], v[218:221], v[22:25]
	v_mfma_f32_16x16x32_f16 v[18:21], v[242:245], v[218:221], v[18:21]
	v_mfma_f32_16x16x32_f16 v[6:9], v[234:237], v[226:229], v[6:9]
	v_mfma_f32_16x16x32_f16 v[2:5], v[242:245], v[226:229], v[2:5]
	v_mfma_f32_16x16x32_f16 v[54:57], v[238:241], v[206:209], v[54:57]
	v_mfma_f32_16x16x32_f16 v[50:53], v[246:249], v[206:209], v[50:53]
	v_mfma_f32_16x16x32_f16 v[38:41], v[238:241], v[214:217], v[38:41]
	v_mfma_f32_16x16x32_f16 v[34:37], v[246:249], v[214:217], v[34:37]
	v_mfma_f32_16x16x32_f16 v[22:25], v[238:241], v[222:225], v[22:25]
	v_mfma_f32_16x16x32_f16 v[18:21], v[246:249], v[222:225], v[18:21]
	v_mfma_f32_16x16x32_f16 v[6:9], v[238:241], v[230:233], v[6:9]
	v_mfma_f32_16x16x32_f16 v[2:5], v[246:249], v[230:233], v[2:5]
	s_setprio 0
	s_barrier
	s_add_u32 s14, s14, 0x40000
	s_addc_u32 s15, s15, 0
	s_mov_b32 m0, s41
	v_lshl_add_u64 v[234:235], s[14:15], 0, v[132:133]
	ds_read_b128 v[202:205], v159 offset:32768
	ds_read_b128 v[206:209], v159 offset:33792
	ds_read_b128 v[210:213], v159 offset:34816
	ds_read_b128 v[214:217], v159 offset:35840
	ds_read_b128 v[218:221], v159 offset:36864
	ds_read_b128 v[222:225], v159 offset:37888
	ds_read_b128 v[226:229], v159 offset:38912
	ds_read_b128 v[230:233], v159 offset:39936
	global_load_lds_dwordx4 v[234:235], off
	v_lshl_add_u64 v[234:235], s[14:15], 0, v[130:131]
	s_mov_b32 m0, s42
	s_nop 0
	global_load_lds_dwordx4 v[234:235], off
	s_waitcnt lgkmcnt(8)
	s_barrier
; #define G8_STAGE(bufoff, gbase) do { _Pragma("unroll") for (int _i = 0; _i < 2; ++_i) \
;     __builtin_amdgcn_global_load_lds((const unsigned*)((const char*)(gbase) + voffA[_i]), (LAS unsigned*)(lds + (bufoff) + ldsw + _i * 8192), 16, 0, 0); } while (0)
; #define G8_LDA(dst, b, h) do { _Pragma("unroll") for (int m = 0; m < 4; ++m) _Pragma("unroll") for (int k = 0; k < 2; ++k) dst[m][k] = *(const LAS h16x8*)(lds + G8_SA(b, h) + aoff + m * 2048 + k * 1024); } while (0)
; #define G8_LDB(dst, b, h) do { _Pragma("unroll") for (int n = 0; n < 2; ++n) _Pragma("unroll") for (int k = 0; k < 2; ++k) dst[n][k] = *(const LAS h16x8*)(lds + G8_SB(b, h) + boff + n * 2048 + k * 1024); } while (0)
; #define G8_WAIT_V(n) asm volatile("s_waitcnt vmcnt(" #n ")" ::: "memory")
; #define G8_BAR __builtin_amdgcn_s_barrier()
; template <class Epi>
; __device__ __forceinline__ void gemm_phase(LAS unsigned char* lds, const h16* A, const h16* Bt, int K, const Order& S, const Epi& E) {
;     ...
;       G8_LDB(B0, 0, 0); G8_SCHED; G8_LDA(At, 0, 0); G8_STAGE(G8_SA(1, 1), a1 + hstep);
;       G8_WAIT_L(8); G8_BAR; G8_WAIT_L(0); G8_MMA(0, 0, At, B0); G8_BAR; G8_SCHED;
;       G8_LDB(B1, 0, 1); G8_STAGE(G8_SB(0, 0), b2);
;       G8_BAR; G8_WAIT_L(0); G8_MMA(0, 1, At, B1); G8_BAR;
;       G8_LDA(At, 0, 1); G8_STAGE(G8_SA(0, 0), a2);
;       G8_BAR; G8_WAIT_L(0); G8_MMA(1, 0, At, B0); G8_BAR; G8_SCHED;
;       G8_STAGE(G8_SB(0, 1), b2 + hstep);
;       G8_WAIT_V(6); G8_BAR; G8_MMA(1, 1, At, B1); G8_BAR;
;       G8_LDB(B0, 1, 0); G8_SCHED; G8_LDA(At, 1, 0); G8_STAGE(G8_SA(0, 1), a2 + hstep);
;       G8_WAIT_L(8); G8_BAR; G8_WAIT_L(0); G8_MMA(0, 0, At, B0); G8_BAR; G8_SCHED;
;       G8_LDB(B1, 1, 1); G8_STAGE(G8_SB(1, 0), b3);
;       G8_BAR; G8_WAIT_L(0); G8_MMA(0, 1, At, B1); G8_BAR;
;       G8_LDA(At, 1, 1); G8_STAGE(G8_SA(1, 0), a3);
;       G8_BAR; G8_WAIT_L(0); G8_MMA(1, 0, At, B0); G8_BAR; G8_SCHED;
;       G8_STAGE(G8_SB(1, 1), b3 + hstep);
;       G8_WAIT_V(6); G8_BAR; G8_MMA(1, 1, At, B1); G8_BAR;
;     }
;     E(acc, cur, ui, wr, wc, fr, fq);
;   __device__ __forceinline__ void operator()(const f32x4 (&acc)[2][2][4][2], const g8::Unit& u, int ui, int wr, int wc, int fr, int fq) const {
;     const int hs = u.pn * 4 + wc;
;     int gi = -1;
;     if (hs < 4) gi = 0; else if (hs < 6) gi = 1; else if (hs >= 16 && hs < 20) gi = 2; else if (hs == 22) gi = 4; else if (hs == 24) gi = 5;
	s_waitcnt lgkmcnt(0)
	s_setprio 1
	s_waitcnt lgkmcnt(0)
	v_mfma_f32_16x16x32_f16 v[126:129], v[152:155], v[202:205], v[126:129]
	v_mfma_f32_16x16x32_f16 v[122:125], v[182:185], v[202:205], v[122:125]
	v_mfma_f32_16x16x32_f16 v[110:113], v[152:155], v[210:213], v[110:113]
	v_mfma_f32_16x16x32_f16 v[106:109], v[182:185], v[210:213], v[106:109]
	v_mfma_f32_16x16x32_f16 v[94:97], v[152:155], v[218:221], v[94:97]
	v_mfma_f32_16x16x32_f16 v[90:93], v[182:185], v[218:221], v[90:93]
	v_mfma_f32_16x16x32_f16 v[78:81], v[152:155], v[226:229], v[78:81]
	v_mfma_f32_16x16x32_f16 v[74:77], v[182:185], v[226:229], v[74:77]
	v_mfma_f32_16x16x32_f16 v[126:129], v[178:181], v[206:209], v[126:129]
	v_mfma_f32_16x16x32_f16 v[122:125], v[186:189], v[206:209], v[122:125]
	v_mfma_f32_16x16x32_f16 v[110:113], v[178:181], v[214:217], v[110:113]
	v_mfma_f32_16x16x32_f16 v[106:109], v[186:189], v[214:217], v[106:109]
	v_mfma_f32_16x16x32_f16 v[94:97], v[178:181], v[222:225], v[94:97]
	v_mfma_f32_16x16x32_f16 v[90:93], v[186:189], v[222:225], v[90:93]
	v_mfma_f32_16x16x32_f16 v[78:81], v[178:181], v[230:233], v[78:81]
	v_mfma_f32_16x16x32_f16 v[74:77], v[186:189], v[230:233], v[74:77]
	s_setprio 0
	s_barrier
	s_mov_b32 m0, s44
	v_lshl_add_u64 v[140:141], v[140:141], 0, s[94:95]
	ds_read_b128 v[234:237], v173
	ds_read_b128 v[238:241], v174
	ds_read_b128 v[242:245], v175
	ds_read_b128 v[246:249], v176
	global_load_lds_dwordx4 v[140:141], off
	v_lshl_add_u64 v[140:141], v[156:157], 0, s[94:95]
	s_mov_b32 m0, s45
	s_nop 0
	global_load_lds_dwordx4 v[140:141], off
	s_barrier
	s_waitcnt lgkmcnt(0)
	s_setprio 1
	s_waitcnt lgkmcnt(0)
	v_mfma_f32_16x16x32_f16 v[118:121], v[234:237], v[202:205], v[118:121]
	v_mfma_f32_16x16x32_f16 v[114:117], v[242:245], v[202:205], v[114:117]
	v_mfma_f32_16x16x32_f16 v[102:105], v[234:237], v[210:213], v[102:105]
	v_mfma_f32_16x16x32_f16 v[98:101], v[242:245], v[210:213], v[98:101]
	v_mfma_f32_16x16x32_f16 v[86:89], v[234:237], v[218:221], v[86:89]
	v_mfma_f32_16x16x32_f16 v[82:85], v[242:245], v[218:221], v[82:85]
	v_mfma_f32_16x16x32_f16 v[70:73], v[234:237], v[226:229], v[70:73]
	v_mfma_f32_16x16x32_f16 v[66:69], v[242:245], v[226:229], v[66:69]
	v_mfma_f32_16x16x32_f16 v[118:121], v[238:241], v[206:209], v[118:121]
	v_mfma_f32_16x16x32_f16 v[114:117], v[246:249], v[206:209], v[114:117]
	v_mfma_f32_16x16x32_f16 v[102:105], v[238:241], v[214:217], v[102:105]
	v_mfma_f32_16x16x32_f16 v[98:101], v[246:249], v[214:217], v[98:101]
	v_mfma_f32_16x16x32_f16 v[86:89], v[238:241], v[222:225], v[86:89]
	v_mfma_f32_16x16x32_f16 v[82:85], v[246:249], v[222:225], v[82:85]
	v_mfma_f32_16x16x32_f16 v[70:73], v[238:241], v[230:233], v[70:73]
	v_mfma_f32_16x16x32_f16 v[66:69], v[246:249], v[230:233], v[66:69]
	s_setprio 0
	s_mov_b32 m0, s46
	v_lshl_add_u64 v[140:141], v[250:251], 0, s[94:95]
	s_barrier
	ds_read_b128 v[202:205], v159 offset:49152
	ds_read_b128 v[206:209], v159 offset:50176
	ds_read_b128 v[210:213], v159 offset:51200
	ds_read_b128 v[214:217], v159 offset:52224
	ds_read_b128 v[218:221], v159 offset:53248
	ds_read_b128 v[222:225], v159 offset:54272
	ds_read_b128 v[226:229], v159 offset:55296
	ds_read_b128 v[230:233], v159 offset:56320
	global_load_lds_dwordx4 v[140:141], off
	v_lshl_add_u64 v[140:141], v[252:253], 0, s[94:95]
	s_mov_b32 m0, s47
	s_nop 0
	global_load_lds_dwordx4 v[140:141], off
	s_waitcnt vmcnt(10)
	s_barrier
	s_waitcnt lgkmcnt(0)
	s_setprio 1
	s_waitcnt lgkmcnt(0)
	v_mfma_f32_16x16x32_f16 v[62:65], v[152:155], v[202:205], v[62:65]
	v_mfma_f32_16x16x32_f16 v[58:61], v[182:185], v[202:205], v[58:61]
	v_mfma_f32_16x16x32_f16 v[46:49], v[152:155], v[210:213], v[46:49]
	v_mfma_f32_16x16x32_f16 v[42:45], v[182:185], v[210:213], v[42:45]
	v_mfma_f32_16x16x32_f16 v[30:33], v[152:155], v[218:221], v[30:33]
	v_mfma_f32_16x16x32_f16 v[26:29], v[182:185], v[218:221], v[26:29]
	v_mfma_f32_16x16x32_f16 v[14:17], v[152:155], v[226:229], v[14:17]
	v_mfma_f32_16x16x32_f16 v[10:13], v[182:185], v[226:229], v[10:13]
	v_mfma_f32_16x16x32_f16 v[62:65], v[178:181], v[206:209], v[62:65]
	v_mfma_f32_16x16x32_f16 v[58:61], v[186:189], v[206:209], v[58:61]
	v_mfma_f32_16x16x32_f16 v[46:49], v[178:181], v[214:217], v[46:49]
	v_mfma_f32_16x16x32_f16 v[42:45], v[186:189], v[214:217], v[42:45]
	v_mfma_f32_16x16x32_f16 v[30:33], v[178:181], v[222:225], v[30:33]
	v_mfma_f32_16x16x32_f16 v[26:29], v[186:189], v[222:225], v[26:29]
	v_mfma_f32_16x16x32_f16 v[14:17], v[178:181], v[230:233], v[14:17]
	v_mfma_f32_16x16x32_f16 v[10:13], v[186:189], v[230:233], v[10:13]
	s_setprio 0
	s_barrier
	s_add_u32 s12, s12, 0x40080
	s_addc_u32 s13, s13, 0
	s_mov_b32 m0, s48
	v_lshl_add_u64 v[140:141], s[12:13], 0, v[132:133]
	global_load_lds_dwordx4 v[140:141], off
	v_lshl_add_u64 v[140:141], s[12:13], 0, v[130:131]
	s_mov_b32 m0, s49
	s_nop 0
	global_load_lds_dwordx4 v[140:141], off
	ds_read_b128 v[152:155], v161
	ds_read_b128 v[178:181], v162
	ds_read_b128 v[182:185], v163
	ds_read_b128 v[186:189], v164
	s_waitcnt vmcnt(6)
	s_barrier
	s_setprio 1
	v_mfma_f32_16x16x32_f16 v[54:57], v[234:237], v[202:205], v[54:57]
	v_mfma_f32_16x16x32_f16 v[50:53], v[242:245], v[202:205], v[50:53]
	v_mfma_f32_16x16x32_f16 v[38:41], v[234:237], v[210:213], v[38:41]
	v_mfma_f32_16x16x32_f16 v[34:37], v[242:245], v[210:213], v[34:37]
	v_mfma_f32_16x16x32_f16 v[22:25], v[234:237], v[218:221], v[22:25]
	v_mfma_f32_16x16x32_f16 v[18:21], v[242:245], v[218:221], v[18:21]
	v_mfma_f32_16x16x32_f16 v[6:9], v[234:237], v[226:229], v[6:9]
	v_mfma_f32_16x16x32_f16 v[2:5], v[242:245], v[226:229], v[2:5]
	v_mfma_f32_16x16x32_f16 v[54:57], v[238:241], v[206:209], v[54:57]
	v_mfma_f32_16x16x32_f16 v[50:53], v[246:249], v[206:209], v[50:53]
	v_mfma_f32_16x16x32_f16 v[38:41], v[238:241], v[214:217], v[38:41]
	v_mfma_f32_16x16x32_f16 v[34:37], v[246:249], v[214:217], v[34:37]
	v_mfma_f32_16x16x32_f16 v[22:25], v[238:241], v[222:225], v[22:25]
	v_mfma_f32_16x16x32_f16 v[18:21], v[246:249], v[222:225], v[18:21]
	v_mfma_f32_16x16x32_f16 v[6:9], v[238:241], v[230:233], v[6:9]
	v_mfma_f32_16x16x32_f16 v[2:5], v[246:249], v[230:233], v[2:5]
	s_setprio 0
	s_add_i32 s54, s54, 2
	s_add_u32 s10, s10, 0x100
	s_addc_u32 s11, s11, 0
	s_add_u32 s27, s27, 0x100
	s_addc_u32 s53, s53, 0
	s_cmp_gt_u32 s54, 13
	s_barrier
	s_cbranch_scc0 .LBB0_195
	s_waitcnt lgkmcnt(0)
	s_lshl_b32 s10, s24, 2
	s_or_b32 s19, s10, s43
	s_cmp_lt_i32 s19, 4
	s_cbranch_scc1 .LBB0_203
	s_cmp_lt_u32 s19, 6
	s_cbranch_scc1 .LBB0_204
	s_cmp_eq_u32 s24, 4
	s_cbranch_scc1 .LBB0_205
	s_cmp_lt_i32 s19, 24
	s_cbranch_scc1 .LBB0_206
	s_cmp_eq_u32 s19, 24
	s_mov_b64 s[10:11], -1
	s_cbranch_scc0 .LBB0_202
	s_mov_b64 s[10:11], 0

; #define G8_STAGE(bufoff, gbase) do { _Pragma("unroll") for (int _i = 0; _i < 2; ++_i) \
;     __builtin_amdgcn_global_load_lds((const unsigned*)((const char*)(gbase) + voffA[_i]), (LAS unsigned*)(lds + (bufoff) + ldsw + _i * 8192), 16, 0, 0); } while (0)
; #define G8_LDA(dst, b, h) do { _Pragma("unroll") for (int m = 0; m < 4; ++m) _Pragma("unroll") for (int k = 0; k < 2; ++k) dst[m][k] = *(const LAS h16x8*)(lds + G8_SA(b, h) + aoff + m * 2048 + k * 1024); } while (0)
; #define G8_LDB(dst, b, h) do { _Pragma("unroll") for (int n = 0; n < 2; ++n) _Pragma("unroll") for (int k = 0; k < 2; ++k) dst[n][k] = *(const LAS h16x8*)(lds + G8_SB(b, h) + boff + n * 2048 + k * 1024); } while (0)
; #define G8_MMA(ai, bj, At, Bt_) do { __builtin_amdgcn_s_setprio(1); _Pragma("unroll") for (int m = 0; m < 4; ++m) _Pragma("unroll") for (int n = 0; n < 2; ++n) _Pragma("unroll") for (int k = 0; k < 2; ++k) \
;     acc[ai][bj][m][n] = __builtin_amdgcn_mfma_f32_16x16x32_f16(Bt_[n][k], At[m][k], acc[ai][bj][m][n], 0, 0, 0); __builtin_amdgcn_s_setprio(0); } while (0)
; #define G8_WAIT_L(n) asm volatile("s_waitcnt lgkmcnt(" #n ")" ::: "memory")
; #define G8_BAR __builtin_amdgcn_s_barrier()
; #define G8_SCHED __builtin_amdgcn_sched_barrier(0)
; template <class Epi>
; __device__ __forceinline__ void gemm_phase(LAS unsigned char* lds, const h16* A, const h16* Bt, int K, const Order& S, const Epi& E) {
;     ...
;     const bool has_next = S.next(ui + 1, nxt);
;     const char* nA = has_next ? (const char*)A + (size_t)nxt.pm * tstep : cA;
;     const char* nB = has_next ? (const char*)Bt + (size_t)nxt.pn * tstep : cB;
;     for (int t = 0; t < nt; t += 2) {
;       const bool last = (t == nt - 2);
;       const char* a1 = cA + (size_t)(t + 1) * kstep;
;       const char* a2 = last ? nA : cA + (size_t)(t + 2) * kstep;
;       const char* b2 = last ? nB : cB + (size_t)(t + 2) * kstep;
;       const char* a3 = a2 + kstep;
;       const char* b3 = b2 + kstep;
;       if (Epi::MID_T >= 0 && t == Epi::MID_T) E.mid(acc, ui, wr, fr);
;       G8_LDB(B0, 0, 0); G8_SCHED; G8_LDA(At, 0, 0); G8_STAGE(G8_SA(1, 1), a1 + hstep);
;       G8_WAIT_L(8); G8_BAR; G8_WAIT_L(0); G8_MMA(0, 0, At, B0); G8_BAR; G8_SCHED;
.LBB0_2541:
	s_ashr_i32 s17, s16, 31
	v_cmp_lt_i64_e32 vcc, s[18:19], v[148:149]
	s_lshl_b64 s[18:19], s[16:17], 21
	s_add_u32 s18, s29, s18
	s_addc_u32 s19, s30, s19
	s_and_b64 s[20:21], vcc, exec
	s_cselect_b32 s3, s19, s23
	s_cselect_b32 s9, s18, s22
	s_ashr_i32 s15, s14, 31
	s_lshl_b64 s[20:21], s[14:15], 21
	s_add_u32 s20, s31, s20
	s_addc_u32 s21, s34, s21
	s_and_b64 s[26:27], vcc, exec
	s_cselect_b32 s15, s21, s25
	s_cselect_b32 s17, s20, s24
	s_add_u32 s22, s22, 0x100080
	s_addc_u32 s23, s23, 0
	s_add_u32 s51, s24, 0x100
	v_mov_b32_e32 v2, 0
	s_addc_u32 s52, s25, 0
	s_mov_b32 s53, -2
	s_waitcnt lgkmcnt(0)
	v_mov_b32_e32 v3, v2
	v_mov_b32_e32 v4, v2
	v_mov_b32_e32 v5, v2
	v_mov_b32_e32 v6, v2
	v_mov_b32_e32 v7, v2
	v_mov_b32_e32 v8, v2
	v_mov_b32_e32 v9, v2
	v_mov_b32_e32 v18, v2
	v_mov_b32_e32 v19, v2
	v_mov_b32_e32 v20, v2
	v_mov_b32_e32 v21, v2
	v_mov_b32_e32 v22, v2
	v_mov_b32_e32 v23, v2
	v_mov_b32_e32 v24, v2
	v_mov_b32_e32 v25, v2
	v_mov_b32_e32 v34, v2
	v_mov_b32_e32 v35, v2
	v_mov_b32_e32 v36, v2
	v_mov_b32_e32 v37, v2
	v_mov_b32_e32 v38, v2
	v_mov_b32_e32 v39, v2
	v_mov_b32_e32 v40, v2
	v_mov_b32_e32 v41, v2
	v_mov_b32_e32 v50, v2
	v_mov_b32_e32 v51, v2
	v_mov_b32_e32 v52, v2
	v_mov_b32_e32 v53, v2
	v_mov_b32_e32 v54, v2
	v_mov_b32_e32 v55, v2
	v_mov_b32_e32 v56, v2
	v_mov_b32_e32 v57, v2
	v_mov_b32_e32 v10, v2
	v_mov_b32_e32 v11, v2
	v_mov_b32_e32 v12, v2
	v_mov_b32_e32 v13, v2
	v_mov_b32_e32 v14, v2
	v_mov_b32_e32 v15, v2
	v_mov_b32_e32 v16, v2
	v_mov_b32_e32 v17, v2
	v_mov_b32_e32 v26, v2
	v_mov_b32_e32 v27, v2
	v_mov_b32_e32 v28, v2
	v_mov_b32_e32 v29, v2
	v_mov_b32_e32 v30, v2
	v_mov_b32_e32 v31, v2
	v_mov_b32_e32 v32, v2
	v_mov_b32_e32 v33, v2
	v_mov_b32_e32 v42, v2
	v_mov_b32_e32 v43, v2
	v_mov_b32_e32 v44, v2
	v_mov_b32_e32 v45, v2
	v_mov_b32_e32 v46, v2
	v_mov_b32_e32 v47, v2
	v_mov_b32_e32 v48, v2
	v_mov_b32_e32 v49, v2
	v_mov_b32_e32 v58, v2
	v_mov_b32_e32 v59, v2
	v_mov_b32_e32 v60, v2
	v_mov_b32_e32 v61, v2
	v_mov_b32_e32 v62, v2
	v_mov_b32_e32 v63, v2
	v_mov_b32_e32 v64, v2
	v_mov_b32_e32 v65, v2
	v_mov_b32_e32 v66, v2
	v_mov_b32_e32 v67, v2
	v_mov_b32_e32 v68, v2
	v_mov_b32_e32 v69, v2
	v_mov_b32_e32 v70, v2
	v_mov_b32_e32 v71, v2
	v_mov_b32_e32 v72, v2
	v_mov_b32_e32 v73, v2
	v_mov_b32_e32 v82, v2
	v_mov_b32_e32 v83, v2
	v_mov_b32_e32 v84, v2
	v_mov_b32_e32 v85, v2
	v_mov_b32_e32 v86, v2
	v_mov_b32_e32 v87, v2
	v_mov_b32_e32 v88, v2
	v_mov_b32_e32 v89, v2
	v_mov_b32_e32 v98, v2
	v_mov_b32_e32 v99, v2
	v_mov_b32_e32 v100, v2
	v_mov_b32_e32 v101, v2
	v_mov_b32_e32 v102, v2
	v_mov_b32_e32 v103, v2
	v_mov_b32_e32 v104, v2
	v_mov_b32_e32 v105, v2
	v_mov_b32_e32 v114, v2
	v_mov_b32_e32 v115, v2
	v_mov_b32_e32 v116, v2
	v_mov_b32_e32 v117, v2
	v_mov_b32_e32 v118, v2
	v_mov_b32_e32 v119, v2
	v_mov_b32_e32 v120, v2
	v_mov_b32_e32 v121, v2
	v_mov_b32_e32 v74, v2
	v_mov_b32_e32 v75, v2
	v_mov_b32_e32 v76, v2
	v_mov_b32_e32 v77, v2
	v_mov_b32_e32 v78, v2
	v_mov_b32_e32 v79, v2
	v_mov_b32_e32 v80, v2
	v_mov_b32_e32 v81, v2
	v_mov_b32_e32 v90, v2
	v_mov_b32_e32 v91, v2
	v_mov_b32_e32 v92, v2
	v_mov_b32_e32 v93, v2
	v_mov_b32_e32 v94, v2
	v_mov_b32_e32 v95, v2
	v_mov_b32_e32 v96, v2
	v_mov_b32_e32 v97, v2
	v_mov_b32_e32 v106, v2
	v_mov_b32_e32 v107, v2
	v_mov_b32_e32 v108, v2
	v_mov_b32_e32 v109, v2
	v_mov_b32_e32 v110, v2
	v_mov_b32_e32 v111, v2
	v_mov_b32_e32 v112, v2
	v_mov_b32_e32 v113, v2
	v_mov_b32_e32 v122, v2
	v_mov_b32_e32 v123, v2
	v_mov_b32_e32 v124, v2
	v_mov_b32_e32 v125, v2
	v_mov_b32_e32 v126, v2
	v_mov_b32_e32 v127, v2
	v_mov_b32_e32 v128, v2
	v_mov_b32_e32 v129, v2
	v_or_b32_e32 v140, 0x10000, v158
	v_add_u32_e32 v141, 0x10400, v158
	ds_read_b128 v[152:155], v140
	ds_read_b128 v[160:163], v141
	v_add_u32_e32 v140, 0x10800, v158
	v_add_u32_e32 v141, 0x10c00, v158
	ds_read_b128 v[164:167], v140
	ds_read_b128 v[168:171], v141
.LBB0_2542:
	s_add_u32 s24, s22, 0xfff00080
	s_addc_u32 s25, s23, -1
	s_cmp_eq_u32 s53, 60
	s_cselect_b32 s27, s3, s25
	s_cselect_b32 s26, s9, s24
	s_cselect_b32 s25, s15, s52
	s_cselect_b32 s24, s17, s51
	v_lshl_add_u64 v[140:141], s[22:23], 0, v[136:137]
	s_add_i32 m0, s35, 0xc000
	ds_read_b128 v[172:175], v135
	ds_read_b128 v[176:179], v135 offset:1024
	ds_read_b128 v[180:183], v135 offset:2048
	ds_read_b128 v[184:187], v135 offset:3072
	ds_read_b128 v[202:205], v135 offset:4096
	ds_read_b128 v[206:209], v135 offset:5120
	ds_read_b128 v[210:213], v135 offset:6144
	ds_read_b128 v[214:217], v135 offset:7168
	global_load_lds_dwordx4 v[140:141], off
	v_lshl_add_u64 v[140:141], s[22:23], 0, v[138:139]
	s_add_i32 m0, s35, 0xe000
	s_nop 0
	global_load_lds_dwordx4 v[140:141], off
	s_waitcnt lgkmcnt(8)
	s_barrier
	s_waitcnt lgkmcnt(0)
	s_setprio 1
	s_waitcnt lgkmcnt(0)
	v_mfma_f32_16x16x32_f16 v[126:129], v[152:155], v[172:175], v[126:129]
	v_mfma_f32_16x16x32_f16 v[122:125], v[164:167], v[172:175], v[122:125]
	v_mfma_f32_16x16x32_f16 v[110:113], v[152:155], v[180:183], v[110:113]
	v_mfma_f32_16x16x32_f16 v[106:109], v[164:167], v[180:183], v[106:109]
	v_mfma_f32_16x16x32_f16 v[94:97], v[152:155], v[202:205], v[94:97]
	v_mfma_f32_16x16x32_f16 v[90:93], v[164:167], v[202:205], v[90:93]
	v_mfma_f32_16x16x32_f16 v[78:81], v[152:155], v[210:213], v[78:81]
	v_mfma_f32_16x16x32_f16 v[74:77], v[164:167], v[210:213], v[74:77]
	v_mfma_f32_16x16x32_f16 v[126:129], v[160:163], v[176:179], v[126:129]
	v_mfma_f32_16x16x32_f16 v[122:125], v[168:171], v[176:179], v[122:125]
	v_mfma_f32_16x16x32_f16 v[110:113], v[160:163], v[184:187], v[110:113]
	v_mfma_f32_16x16x32_f16 v[106:109], v[168:171], v[184:187], v[106:109]
	v_mfma_f32_16x16x32_f16 v[94:97], v[160:163], v[206:209], v[94:97]
	v_mfma_f32_16x16x32_f16 v[90:93], v[168:171], v[206:209], v[90:93]
	v_mfma_f32_16x16x32_f16 v[78:81], v[160:163], v[214:217], v[78:81]
	v_mfma_f32_16x16x32_f16 v[74:77], v[168:171], v[214:217], v[74:77]
	s_setprio 0
	s_barrier
; #define G8_STAGE(bufoff, gbase) do { _Pragma("unroll") for (int _i = 0; _i < 2; ++_i) \
;     __builtin_amdgcn_global_load_lds((const unsigned*)((const char*)(gbase) + voffA[_i]), (LAS unsigned*)(lds + (bufoff) + ldsw + _i * 8192), 16, 0, 0); } while (0)
; #define G8_LDA(dst, b, h) do { _Pragma("unroll") for (int m = 0; m < 4; ++m) _Pragma("unroll") for (int k = 0; k < 2; ++k) dst[m][k] = *(const LAS h16x8*)(lds + G8_SA(b, h) + aoff + m * 2048 + k * 1024); } while (0)
; #define G8_LDB(dst, b, h) do { _Pragma("unroll") for (int n = 0; n < 2; ++n) _Pragma("unroll") for (int k = 0; k < 2; ++k) dst[n][k] = *(const LAS h16x8*)(lds + G8_SB(b, h) + boff + n * 2048 + k * 1024); } while (0)
; #define G8_MMA(ai, bj, At, Bt_) do { __builtin_amdgcn_s_setprio(1); _Pragma("unroll") for (int m = 0; m < 4; ++m) _Pragma("unroll") for (int n = 0; n < 2; ++n) _Pragma("unroll") for (int k = 0; k < 2; ++k) \
;     acc[ai][bj][m][n] = __builtin_amdgcn_mfma_f32_16x16x32_f16(Bt_[n][k], At[m][k], acc[ai][bj][m][n], 0, 0, 0); __builtin_amdgcn_s_setprio(0); } while (0)
; #define G8_WAIT_V(n) asm volatile("s_waitcnt vmcnt(" #n ")" ::: "memory")
; #define G8_WAIT_L(n) asm volatile("s_waitcnt lgkmcnt(" #n ")" ::: "memory")
; #define G8_BAR __builtin_amdgcn_s_barrier()
; #define G8_SCHED __builtin_amdgcn_sched_barrier(0)
; template <class Epi>
; __device__ __forceinline__ void gemm_phase(LAS unsigned char* lds, const h16* A, const h16* Bt, int K, const Order& S, const Epi& E) {
;     ...
;       G8_LDB(B1, 0, 1); G8_STAGE(G8_SB(0, 0), b2);
;       G8_BAR; G8_WAIT_L(0); G8_MMA(0, 1, At, B1); G8_BAR;
;       G8_LDA(At, 0, 1); G8_STAGE(G8_SA(0, 0), a2);
;       G8_BAR; G8_WAIT_L(0); G8_MMA(1, 0, At, B0); G8_BAR; G8_SCHED;
;       G8_STAGE(G8_SB(0, 1), b2 + hstep);
;       G8_WAIT_V(6); G8_BAR; G8_MMA(1, 1, At, B1); G8_BAR;
;       G8_LDB(B0, 1, 0); G8_SCHED; G8_LDA(At, 1, 0); G8_STAGE(G8_SA(0, 1), a2 + hstep);
;       G8_WAIT_L(8); G8_BAR; G8_WAIT_L(0); G8_MMA(0, 0, At, B0); G8_BAR; G8_SCHED;
	v_or_b32_e32 v140, 0x14000, v158
	v_add_u32_e32 v141, 0x14400, v158
	ds_read_b128 v[218:221], v140
	ds_read_b128 v[222:225], v141
	v_add_u32_e32 v140, 0x14800, v158
	v_add_u32_e32 v141, 0x14c00, v158
	s_mov_b32 m0, s36
	ds_read_b128 v[226:229], v140
	ds_read_b128 v[230:233], v141
	v_lshl_add_u64 v[140:141], s[24:25], 0, v[0:1]
	global_load_lds_dwordx4 v[140:141], off
	v_lshl_add_u64 v[156:157], s[24:25], 0, v[130:131]
	s_mov_b32 m0, s37
	s_nop 0
	global_load_lds_dwordx4 v[156:157], off
	s_barrier
	s_waitcnt lgkmcnt(0)
	s_setprio 1
	s_waitcnt lgkmcnt(0)
	v_mfma_f32_16x16x32_f16 v[118:121], v[218:221], v[172:175], v[118:121]
	v_mfma_f32_16x16x32_f16 v[114:117], v[226:229], v[172:175], v[114:117]
	v_mfma_f32_16x16x32_f16 v[102:105], v[218:221], v[180:183], v[102:105]
	v_mfma_f32_16x16x32_f16 v[98:101], v[226:229], v[180:183], v[98:101]
	v_mfma_f32_16x16x32_f16 v[86:89], v[218:221], v[202:205], v[86:89]
	v_mfma_f32_16x16x32_f16 v[82:85], v[226:229], v[202:205], v[82:85]
	v_mfma_f32_16x16x32_f16 v[70:73], v[218:221], v[210:213], v[70:73]
	v_mfma_f32_16x16x32_f16 v[66:69], v[226:229], v[210:213], v[66:69]
	v_mfma_f32_16x16x32_f16 v[118:121], v[222:225], v[176:179], v[118:121]
	v_mfma_f32_16x16x32_f16 v[114:117], v[230:233], v[176:179], v[114:117]
	v_mfma_f32_16x16x32_f16 v[102:105], v[222:225], v[184:187], v[102:105]
	v_mfma_f32_16x16x32_f16 v[98:101], v[230:233], v[184:187], v[98:101]
	v_mfma_f32_16x16x32_f16 v[86:89], v[222:225], v[206:209], v[86:89]
	v_mfma_f32_16x16x32_f16 v[82:85], v[230:233], v[206:209], v[82:85]
	v_mfma_f32_16x16x32_f16 v[70:73], v[222:225], v[214:217], v[70:73]
	v_mfma_f32_16x16x32_f16 v[66:69], v[230:233], v[214:217], v[66:69]
	s_setprio 0
	s_mov_b32 m0, s35
	v_lshl_add_u64 v[188:189], s[26:27], 0, v[0:1]
	s_barrier
	ds_read_b128 v[172:175], v135 offset:16384
	ds_read_b128 v[176:179], v135 offset:17408
	ds_read_b128 v[180:183], v135 offset:18432
	ds_read_b128 v[184:187], v135 offset:19456
	ds_read_b128 v[202:205], v135 offset:20480
	ds_read_b128 v[206:209], v135 offset:21504
	ds_read_b128 v[210:213], v135 offset:22528
	ds_read_b128 v[214:217], v135 offset:23552
	global_load_lds_dwordx4 v[188:189], off
	v_lshl_add_u64 v[234:235], s[26:27], 0, v[130:131]
	s_mov_b32 m0, s38
	s_nop 0
	global_load_lds_dwordx4 v[234:235], off
	s_waitcnt vmcnt(10)
	s_barrier
	s_waitcnt lgkmcnt(0)
	s_setprio 1
	s_waitcnt lgkmcnt(0)
	v_mfma_f32_16x16x32_f16 v[62:65], v[152:155], v[172:175], v[62:65]
	v_mfma_f32_16x16x32_f16 v[58:61], v[164:167], v[172:175], v[58:61]
	v_mfma_f32_16x16x32_f16 v[46:49], v[152:155], v[180:183], v[46:49]
	v_mfma_f32_16x16x32_f16 v[42:45], v[164:167], v[180:183], v[42:45]
	v_mfma_f32_16x16x32_f16 v[30:33], v[152:155], v[202:205], v[30:33]
	v_mfma_f32_16x16x32_f16 v[26:29], v[164:167], v[202:205], v[26:29]
	v_mfma_f32_16x16x32_f16 v[14:17], v[152:155], v[210:213], v[14:17]
	v_mfma_f32_16x16x32_f16 v[10:13], v[164:167], v[210:213], v[10:13]
	v_mfma_f32_16x16x32_f16 v[62:65], v[160:163], v[176:179], v[62:65]
	v_mfma_f32_16x16x32_f16 v[58:61], v[168:171], v[176:179], v[58:61]
	v_mfma_f32_16x16x32_f16 v[46:49], v[160:163], v[184:187], v[46:49]
	v_mfma_f32_16x16x32_f16 v[42:45], v[168:171], v[184:187], v[42:45]
	v_mfma_f32_16x16x32_f16 v[30:33], v[160:163], v[206:209], v[30:33]
	v_mfma_f32_16x16x32_f16 v[26:29], v[168:171], v[206:209], v[26:29]
	v_mfma_f32_16x16x32_f16 v[14:17], v[160:163], v[214:217], v[14:17]
	v_mfma_f32_16x16x32_f16 v[10:13], v[168:171], v[214:217], v[10:13]
	s_setprio 0
	s_barrier
	s_add_u32 s54, s24, 0x100000
	s_addc_u32 s55, s25, 0
	s_mov_b32 m0, s39
	v_lshl_add_u64 v[152:153], s[54:55], 0, v[0:1]
	global_load_lds_dwordx4 v[152:153], off
	v_lshl_add_u64 v[152:153], s[54:55], 0, v[130:131]
	s_mov_b32 m0, s40
	s_nop 0
	global_load_lds_dwordx4 v[152:153], off
	v_or_b32_e32 v152, 0x18000, v158
	v_add_u32_e32 v159, 0x18400, v158
	ds_read_b128 v[152:155], v152
	ds_read_b128 v[160:163], v159
	v_add_u32_e32 v159, 0x18800, v158
	v_add_u32_e32 v168, 0x18c00, v158
	ds_read_b128 v[164:167], v159
	ds_read_b128 v[168:171], v168
	s_waitcnt vmcnt(6)
	s_barrier
	s_setprio 1
	v_mfma_f32_16x16x32_f16 v[54:57], v[218:221], v[172:175], v[54:57]
	v_mfma_f32_16x16x32_f16 v[50:53], v[226:229], v[172:175], v[50:53]
	v_mfma_f32_16x16x32_f16 v[38:41], v[218:221], v[180:183], v[38:41]
	v_mfma_f32_16x16x32_f16 v[34:37], v[226:229], v[180:183], v[34:37]
	v_mfma_f32_16x16x32_f16 v[22:25], v[218:221], v[202:205], v[22:25]
	v_mfma_f32_16x16x32_f16 v[18:21], v[226:229], v[202:205], v[18:21]
	v_mfma_f32_16x16x32_f16 v[6:9], v[218:221], v[210:213], v[6:9]
	v_mfma_f32_16x16x32_f16 v[2:5], v[226:229], v[210:213], v[2:5]
	v_mfma_f32_16x16x32_f16 v[54:57], v[222:225], v[176:179], v[54:57]
	v_mfma_f32_16x16x32_f16 v[50:53], v[230:233], v[176:179], v[50:53]
	v_mfma_f32_16x16x32_f16 v[38:41], v[222:225], v[184:187], v[38:41]
	v_mfma_f32_16x16x32_f16 v[34:37], v[230:233], v[184:187], v[34:37]
	v_mfma_f32_16x16x32_f16 v[22:25], v[222:225], v[206:209], v[22:25]
	v_mfma_f32_16x16x32_f16 v[18:21], v[230:233], v[206:209], v[18:21]
	v_mfma_f32_16x16x32_f16 v[6:9], v[222:225], v[214:217], v[6:9]
	v_mfma_f32_16x16x32_f16 v[2:5], v[230:233], v[214:217], v[2:5]
	s_setprio 0
	s_barrier
	s_add_u32 s26, s26, 0x100000
	s_addc_u32 s27, s27, 0
	s_mov_b32 m0, s41
	v_lshl_add_u64 v[218:219], s[26:27], 0, v[0:1]
	ds_read_b128 v[172:175], v135 offset:32768
	ds_read_b128 v[176:179], v135 offset:33792
	ds_read_b128 v[180:183], v135 offset:34816
	ds_read_b128 v[184:187], v135 offset:35840
	ds_read_b128 v[202:205], v135 offset:36864
	ds_read_b128 v[206:209], v135 offset:37888
	ds_read_b128 v[210:213], v135 offset:38912
	ds_read_b128 v[214:217], v135 offset:39936
	global_load_lds_dwordx4 v[218:219], off
	v_lshl_add_u64 v[218:219], s[26:27], 0, v[130:131]
	s_mov_b32 m0, s42
	s_nop 0
	global_load_lds_dwordx4 v[218:219], off
	s_waitcnt lgkmcnt(8)
	s_barrier
; #define G8_STAGE(bufoff, gbase) do { _Pragma("unroll") for (int _i = 0; _i < 2; ++_i) \
;     __builtin_amdgcn_global_load_lds((const unsigned*)((const char*)(gbase) + voffA[_i]), (LAS unsigned*)(lds + (bufoff) + ldsw + _i * 8192), 16, 0, 0); } while (0)
; #define G8_LDA(dst, b, h) do { _Pragma("unroll") for (int m = 0; m < 4; ++m) _Pragma("unroll") for (int k = 0; k < 2; ++k) dst[m][k] = *(const LAS h16x8*)(lds + G8_SA(b, h) + aoff + m * 2048 + k * 1024); } while (0)
; #define G8_LDB(dst, b, h) do { _Pragma("unroll") for (int n = 0; n < 2; ++n) _Pragma("unroll") for (int k = 0; k < 2; ++k) dst[n][k] = *(const LAS h16x8*)(lds + G8_SB(b, h) + boff + n * 2048 + k * 1024); } while (0)
; #define G8_MMA(ai, bj, At, Bt_) do { __builtin_amdgcn_s_setprio(1); _Pragma("unroll") for (int m = 0; m < 4; ++m) _Pragma("unroll") for (int n = 0; n < 2; ++n) _Pragma("unroll") for (int k = 0; k < 2; ++k) \
;     acc[ai][bj][m][n] = __builtin_amdgcn_mfma_f32_16x16x32_f16(Bt_[n][k], At[m][k], acc[ai][bj][m][n], 0, 0, 0); __builtin_amdgcn_s_setprio(0); } while (0)
; #define G8_WAIT_L(n) asm volatile("s_waitcnt lgkmcnt(" #n ")" ::: "memory")
; #define G8_BAR __builtin_amdgcn_s_barrier()
; #define G8_SCHED __builtin_amdgcn_sched_barrier(0)
; template <class Epi>
; __device__ __forceinline__ void gemm_phase(LAS unsigned char* lds, const h16* A, const h16* Bt, int K, const Order& S, const Epi& E) {
;     ...
;       G8_WAIT_L(8); G8_BAR; G8_WAIT_L(0); G8_MMA(0, 0, At, B0); G8_BAR; G8_SCHED;
;       G8_LDB(B1, 1, 1); G8_STAGE(G8_SB(1, 0), b3);
;       G8_BAR; G8_WAIT_L(0); G8_MMA(0, 1, At, B1); G8_BAR;
;       G8_LDA(At, 1, 1); G8_STAGE(G8_SA(1, 0), a3);
;       G8_BAR; G8_WAIT_L(0); G8_MMA(1, 0, At, B0); G8_BAR; G8_SCHED;
	s_waitcnt lgkmcnt(0)
	s_setprio 1
	s_waitcnt lgkmcnt(0)
	v_mfma_f32_16x16x32_f16 v[126:129], v[152:155], v[172:175], v[126:129]
	v_mfma_f32_16x16x32_f16 v[122:125], v[164:167], v[172:175], v[122:125]
	v_mfma_f32_16x16x32_f16 v[110:113], v[152:155], v[180:183], v[110:113]
	v_mfma_f32_16x16x32_f16 v[106:109], v[164:167], v[180:183], v[106:109]
	v_mfma_f32_16x16x32_f16 v[94:97], v[152:155], v[202:205], v[94:97]
	v_mfma_f32_16x16x32_f16 v[90:93], v[164:167], v[202:205], v[90:93]
	v_mfma_f32_16x16x32_f16 v[78:81], v[152:155], v[210:213], v[78:81]
	v_mfma_f32_16x16x32_f16 v[74:77], v[164:167], v[210:213], v[74:77]
	v_mfma_f32_16x16x32_f16 v[126:129], v[160:163], v[176:179], v[126:129]
	v_mfma_f32_16x16x32_f16 v[122:125], v[168:171], v[176:179], v[122:125]
	v_mfma_f32_16x16x32_f16 v[110:113], v[160:163], v[184:187], v[110:113]
	v_mfma_f32_16x16x32_f16 v[106:109], v[168:171], v[184:187], v[106:109]
	v_mfma_f32_16x16x32_f16 v[94:97], v[160:163], v[206:209], v[94:97]
	v_mfma_f32_16x16x32_f16 v[90:93], v[168:171], v[206:209], v[90:93]
	v_mfma_f32_16x16x32_f16 v[78:81], v[160:163], v[214:217], v[78:81]
	v_mfma_f32_16x16x32_f16 v[74:77], v[168:171], v[214:217], v[74:77]
	s_setprio 0
	s_barrier
	v_or_b32_e32 v159, 0x1c000, v158
	s_mov_b32 m0, s44
	v_add_u32_e32 v195, 0x1c400, v158
	ds_read_b128 v[218:221], v159
	ds_read_b128 v[222:225], v195
	v_add_u32_e32 v159, 0x1c800, v158
	v_lshl_add_u64 v[140:141], v[140:141], 0, s[94:95]
	v_add_u32_e32 v195, 0x1cc00, v158
	ds_read_b128 v[226:229], v159
	ds_read_b128 v[230:233], v195
	global_load_lds_dwordx4 v[140:141], off
	v_lshl_add_u64 v[140:141], v[156:157], 0, s[94:95]
	s_mov_b32 m0, s45
	s_nop 0
	global_load_lds_dwordx4 v[140:141], off
	s_barrier
	s_waitcnt lgkmcnt(0)
	s_setprio 1
	s_waitcnt lgkmcnt(0)
	v_mfma_f32_16x16x32_f16 v[118:121], v[218:221], v[172:175], v[118:121]
	v_mfma_f32_16x16x32_f16 v[114:117], v[226:229], v[172:175], v[114:117]
	v_mfma_f32_16x16x32_f16 v[102:105], v[218:221], v[180:183], v[102:105]
	v_mfma_f32_16x16x32_f16 v[98:101], v[226:229], v[180:183], v[98:101]
	v_mfma_f32_16x16x32_f16 v[86:89], v[218:221], v[202:205], v[86:89]
	v_mfma_f32_16x16x32_f16 v[82:85], v[226:229], v[202:205], v[82:85]
	v_mfma_f32_16x16x32_f16 v[70:73], v[218:221], v[210:213], v[70:73]
	v_mfma_f32_16x16x32_f16 v[66:69], v[226:229], v[210:213], v[66:69]
	v_mfma_f32_16x16x32_f16 v[118:121], v[222:225], v[176:179], v[118:121]
	v_mfma_f32_16x16x32_f16 v[114:117], v[230:233], v[176:179], v[114:117]
	v_mfma_f32_16x16x32_f16 v[102:105], v[222:225], v[184:187], v[102:105]
	v_mfma_f32_16x16x32_f16 v[98:101], v[230:233], v[184:187], v[98:101]
	v_mfma_f32_16x16x32_f16 v[86:89], v[222:225], v[206:209], v[86:89]
	v_mfma_f32_16x16x32_f16 v[82:85], v[230:233], v[206:209], v[82:85]
	v_mfma_f32_16x16x32_f16 v[70:73], v[222:225], v[214:217], v[70:73]
	v_mfma_f32_16x16x32_f16 v[66:69], v[230:233], v[214:217], v[66:69]
	s_setprio 0
	s_mov_b32 m0, s46
	v_lshl_add_u64 v[140:141], v[188:189], 0, s[94:95]
	s_barrier
	ds_read_b128 v[172:175], v135 offset:49152
	ds_read_b128 v[176:179], v135 offset:50176
	ds_read_b128 v[180:183], v135 offset:51200
	ds_read_b128 v[184:187], v135 offset:52224
	ds_read_b128 v[202:205], v135 offset:53248
	ds_read_b128 v[206:209], v135 offset:54272
	ds_read_b128 v[210:213], v135 offset:55296
	ds_read_b128 v[214:217], v135 offset:56320
	global_load_lds_dwordx4 v[140:141], off
	v_lshl_add_u64 v[140:141], v[234:235], 0, s[94:95]
	s_mov_b32 m0, s47
	s_nop 0
	global_load_lds_dwordx4 v[140:141], off
	s_waitcnt vmcnt(10)
	s_barrier
	s_waitcnt lgkmcnt(0)
	s_setprio 1
	s_waitcnt lgkmcnt(0)
	v_mfma_f32_16x16x32_f16 v[62:65], v[152:155], v[172:175], v[62:65]
	v_mfma_f32_16x16x32_f16 v[58:61], v[164:167], v[172:175], v[58:61]
	v_mfma_f32_16x16x32_f16 v[46:49], v[152:155], v[180:183], v[46:49]
	v_mfma_f32_16x16x32_f16 v[42:45], v[164:167], v[180:183], v[42:45]
	v_mfma_f32_16x16x32_f16 v[30:33], v[152:155], v[202:205], v[30:33]
	v_mfma_f32_16x16x32_f16 v[26:29], v[164:167], v[202:205], v[26:29]
	v_mfma_f32_16x16x32_f16 v[14:17], v[152:155], v[210:213], v[14:17]
	v_mfma_f32_16x16x32_f16 v[10:13], v[164:167], v[210:213], v[10:13]
	v_mfma_f32_16x16x32_f16 v[62:65], v[160:163], v[176:179], v[62:65]
	v_mfma_f32_16x16x32_f16 v[58:61], v[168:171], v[176:179], v[58:61]
	v_mfma_f32_16x16x32_f16 v[46:49], v[160:163], v[184:187], v[46:49]
	v_mfma_f32_16x16x32_f16 v[42:45], v[168:171], v[184:187], v[42:45]
	v_mfma_f32_16x16x32_f16 v[30:33], v[160:163], v[206:209], v[30:33]
	v_mfma_f32_16x16x32_f16 v[26:29], v[168:171], v[206:209], v[26:29]
	v_mfma_f32_16x16x32_f16 v[14:17], v[160:163], v[214:217], v[14:17]
	v_mfma_f32_16x16x32_f16 v[10:13], v[168:171], v[214:217], v[10:13]
	s_setprio 0
	s_barrier
; #define G8_STAGE(bufoff, gbase) do { _Pragma("unroll") for (int _i = 0; _i < 2; ++_i) \
;     __builtin_amdgcn_global_load_lds((const unsigned*)((const char*)(gbase) + voffA[_i]), (LAS unsigned*)(lds + (bufoff) + ldsw + _i * 8192), 16, 0, 0); } while (0)
; #define G8_MMA(ai, bj, At, Bt_) do { __builtin_amdgcn_s_setprio(1); _Pragma("unroll") for (int m = 0; m < 4; ++m) _Pragma("unroll") for (int n = 0; n < 2; ++n) _Pragma("unroll") for (int k = 0; k < 2; ++k) \
;     acc[ai][bj][m][n] = __builtin_amdgcn_mfma_f32_16x16x32_f16(Bt_[n][k], At[m][k], acc[ai][bj][m][n], 0, 0, 0); __builtin_amdgcn_s_setprio(0); } while (0)
; #define G8_WAIT_V(n) asm volatile("s_waitcnt vmcnt(" #n ")" ::: "memory")
; #define G8_BAR __builtin_amdgcn_s_barrier()
; template <class Epi>
; __device__ __forceinline__ void gemm_phase(LAS unsigned char* lds, const h16* A, const h16* Bt, int K, const Order& S, const Epi& E) {
;     ...
;       G8_STAGE(G8_SB(1, 1), b3 + hstep);
;       G8_WAIT_V(6); G8_BAR; G8_MMA(1, 1, At, B1); G8_BAR;
;     }
;     E(acc, cur, ui, wr, wc, fr, fq);
;   __device__ __forceinline__ void operator()(const f32x4 (&acc)[2][2][4][2], const g8::Unit& u, int ui, int wr, int wc, int fr, int fq) const {
; #pragma unroll
;     for (int ai = 0; ai < 2; ++ai)
; #pragma unroll
;       for (int m = 0; m < 4; ++m) {
;         const size_t row = (size_t)u.pm * 256 + 128 * ai + 64 * wr + 16 * m + fr;
;         const size_t base = row * DM + 256 * u.pn + 32 * wc + 8 * fq;
;         float ss = 0.f;
; #pragma unroll
;         for (int bj = 0; bj < 2; ++bj) {
;           const size_t idx = base + 128 * bj;
;           const h16x8 xv = *(const h16x8*)(xb + idx);
;           f32x4 x0 = acc[ai][bj][m][0], x1 = acc[ai][bj][m][1];
; #pragma unroll
;           for (int j = 0; j < 4; ++j) { x0[j] += (float)xv[j]; x1[j] += (float)xv[4 + j]; ss += x0[j] * x0[j] + x1[j] * x1[j]; }
;           if (final_out) {
;             __builtin_nontemporal_store(x0, (f32x4*)(xo + idx));
;             __builtin_nontemporal_store(x1, (f32x4*)(xo + idx + 4));
;           } else {
;             *(h16x8*)(xb + idx) = pack8(x0, x1);
	s_add_u32 s24, s24, 0x100080
	s_addc_u32 s25, s25, 0
	s_mov_b32 m0, s48
	v_lshl_add_u64 v[140:141], s[24:25], 0, v[0:1]
	global_load_lds_dwordx4 v[140:141], off
	v_lshl_add_u64 v[140:141], s[24:25], 0, v[130:131]
	s_mov_b32 m0, s49
	s_nop 0
	global_load_lds_dwordx4 v[140:141], off
	v_or_b32_e32 v140, 0x10000, v158
	v_add_u32_e32 v141, 0x10400, v158
	ds_read_b128 v[152:155], v140
	ds_read_b128 v[160:163], v141
	v_add_u32_e32 v140, 0x10800, v158
	v_add_u32_e32 v141, 0x10c00, v158
	ds_read_b128 v[164:167], v140
	ds_read_b128 v[168:171], v141
	s_waitcnt vmcnt(6)
	s_barrier
	s_setprio 1
	v_mfma_f32_16x16x32_f16 v[54:57], v[218:221], v[172:175], v[54:57]
	v_mfma_f32_16x16x32_f16 v[50:53], v[226:229], v[172:175], v[50:53]
	v_mfma_f32_16x16x32_f16 v[38:41], v[218:221], v[180:183], v[38:41]
	v_mfma_f32_16x16x32_f16 v[34:37], v[226:229], v[180:183], v[34:37]
	v_mfma_f32_16x16x32_f16 v[22:25], v[218:221], v[202:205], v[22:25]
	v_mfma_f32_16x16x32_f16 v[18:21], v[226:229], v[202:205], v[18:21]
	v_mfma_f32_16x16x32_f16 v[6:9], v[218:221], v[210:213], v[6:9]
	v_mfma_f32_16x16x32_f16 v[2:5], v[226:229], v[210:213], v[2:5]
	v_mfma_f32_16x16x32_f16 v[54:57], v[222:225], v[176:179], v[54:57]
	v_mfma_f32_16x16x32_f16 v[50:53], v[230:233], v[176:179], v[50:53]
	v_mfma_f32_16x16x32_f16 v[38:41], v[222:225], v[184:187], v[38:41]
	v_mfma_f32_16x16x32_f16 v[34:37], v[230:233], v[184:187], v[34:37]
	v_mfma_f32_16x16x32_f16 v[22:25], v[222:225], v[206:209], v[22:25]
	v_mfma_f32_16x16x32_f16 v[18:21], v[230:233], v[206:209], v[18:21]
	v_mfma_f32_16x16x32_f16 v[6:9], v[222:225], v[214:217], v[6:9]
	v_mfma_f32_16x16x32_f16 v[2:5], v[230:233], v[214:217], v[2:5]
	s_setprio 0
	s_add_i32 s53, s53, 2
	s_add_u32 s22, s22, 0x100
	s_addc_u32 s23, s23, 0
	s_add_u32 s51, s51, 0x100
	s_addc_u32 s52, s52, 0
	s_cmp_gt_u32 s53, 61
	s_barrier
	s_cbranch_scc0 .LBB0_2542
	s_waitcnt lgkmcnt(0)
	s_ashr_i32 s9, s8, 31
	s_lshl_b64 s[8:9], s[8:9], 8
	s_lshl_b32 s3, s2, 8
	v_lshl_add_u64 v[140:141], s[8:9], 0, v[132:133]
	s_ashr_i32 s8, s3, 31
	v_mov_b32_e32 v153, s8
	v_or_b32_e32 v152, s3, v134
	v_lshlrev_b64 v[154:155], 10, v[140:141]
	v_lshl_add_u64 v[156:157], v[154:155], 0, v[152:153]
	v_lshl_add_u64 v[154:155], v[156:157], 1, s[10:11]
	global_load_dwordx4 v[166:169], v[154:155], off
	global_load_dwordx4 v[170:173], v[154:155], off offset:256
	s_mov_b32 s9, 0
	s_mov_b32 s8, 0x8000
	v_lshl_add_u64 v[234:235], v[154:155], 0, s[8:9]
	global_load_dwordx4 v[174:177], v[234:235], off
	global_load_dwordx4 v[178:181], v[234:235], off offset:256
	s_mov_b32 s8, 0x10000
	v_lshl_add_u64 v[234:235], v[154:155], 0, s[8:9]
	global_load_dwordx4 v[182:185], v[234:235], off
	global_load_dwordx4 v[186:189], v[234:235], off offset:256
	s_mov_b32 s8, 0x18000
	v_lshl_add_u64 v[234:235], v[154:155], 0, s[8:9]
	global_load_dwordx4 v[202:205], v[234:235], off
	global_load_dwordx4 v[206:209], v[234:235], off offset:256
	s_mov_b32 s8, 0x40000
	v_lshl_add_u64 v[234:235], v[154:155], 0, s[8:9]
	global_load_dwordx4 v[210:213], v[234:235], off
	global_load_dwordx4 v[214:217], v[234:235], off offset:256
	s_mov_b32 s8, 0x48000
	v_lshl_add_u64 v[234:235], v[154:155], 0, s[8:9]
	global_load_dwordx4 v[218:221], v[234:235], off
	global_load_dwordx4 v[222:225], v[234:235], off offset:256
	s_mov_b32 s8, 0x50000
	v_lshl_add_u64 v[234:235], v[154:155], 0, s[8:9]
	global_load_dwordx4 v[226:229], v[234:235], off
	global_load_dwordx4 v[230:233], v[234:235], off offset:256
	s_mov_b64 s[8:9], -1
	s_and_b64 vcc, exec, s[0:1]
	s_waitcnt vmcnt(13)
	v_cvt_f32_f16_e32 v164, v166
	v_cvt_f32_f16_sdwa v165, v166 dst_sel:DWORD dst_unused:UNUSED_PAD src0_sel:WORD_1
	v_cvt_f32_f16_e32 v160, v167
	v_cvt_f32_f16_sdwa v161, v167 dst_sel:DWORD dst_unused:UNUSED_PAD src0_sel:WORD_1
	v_pk_add_f32 v[126:127], v[126:127], v[164:165]
	v_cvt_f32_f16_e32 v164, v168
	v_cvt_f32_f16_sdwa v165, v168 dst_sel:DWORD dst_unused:UNUSED_PAD src0_sel:WORD_1
	v_pk_add_f32 v[128:129], v[128:129], v[160:161]
	v_cvt_f32_f16_e32 v160, v169
	v_cvt_f32_f16_sdwa v161, v169 dst_sel:DWORD dst_unused:UNUSED_PAD src0_sel:WORD_1
	v_pk_add_f32 v[122:123], v[122:123], v[164:165]
	v_pk_add_f32 v[124:125], v[124:125], v[160:161]
	s_cbranch_vccz .LBB0_2545
	v_cvt_pk_f16_f32 v163, v124, v125
	v_cvt_pk_f16_f32 v162, v122, v123
	v_cvt_pk_f16_f32 v161, v128, v129
	v_cvt_pk_f16_f32 v160, v126, v127
	global_store_dwordx4 v[154:155], v[160:163], off
	s_mov_b64 s[8:9], 0
